# branch phase job placement: S5 jobs on the workgroups of XCDs 0-1, mLSTM on XCDs 2-7 (was interleaved on every XCD)
# speedup vs baseline: 1.0042x; 1.0042x over previous
;   __shared__ int sjob;
;   if (mode & 1)
;   for (int jb = blockIdx.x; jb < 176; jb += gridDim.x) {
;     if (jb < 48) { if (EN & 16) s5_job(p, l, jb, smem); }
;     else { if (EN & 32) mlstm_job(p, l, jb - 48, smem); }
;   }
.LBB0_421:
	s_mov_b64 s[0:1], 0
	v_writelane_b32 v255, s0, 22
	s_andn2_b64 vcc, exec, s[4:5]
	s_nop 0
	v_writelane_b32 v255, s1, 23
	s_cbranch_vccnz .LBB0_605
	v_readlane_b32 s0, v255, 24
	s_cmp_gt_i32 s0, 0
	s_mov_b64 s[4:5], -1
	s_cbranch_scc0 .LBB0_603
	v_readlane_b32 s0, v252, 0
	s_cmpk_lg_i32 s83, 0x100
	s_cbranch_scc1 .Ljm_plain
	s_and_b32 s38, s0, 7
	s_lshr_b32 vcc_lo, s0, 3
	s_cmp_lt_u32 s38, 2
	s_cbranch_scc0 .Ljm_ml
	s_lshl_b32 vcc_lo, vcc_lo, 1
	s_add_i32 s38, s38, vcc_lo
	s_cmp_lt_u32 s38, 48
	s_cselect_b32 s38, s38, 0x100
	s_branch .Ljm_done
.Ljm_ml:
	s_mul_i32 vcc_lo, vcc_lo, 6
	s_add_i32 s38, s38, vcc_lo
	s_add_i32 s38, s38, 46
	s_cmpk_lt_u32 s38, 0xb0
	s_cselect_b32 s38, s38, 0x100
	s_branch .Ljm_done
.Ljm_plain:
	s_mov_b32 s38, s0
.Ljm_done:
	v_readlane_b32 s0, v255, 20
	s_mul_i32 s70, s0, 0x600
	v_readlane_b32 s1, v255, 21
	s_cmpk_lt_i32 s38, 0xb0
	s_cbranch_scc0 .LBB0_514
	v_readlane_b32 s0, v255, 20
	s_mul_i32 s71, s0, 0x1200
	s_add_i32 s73, s71, 0x600
	s_add_i32 s43, s71, 0xc00
	s_lshl_b32 s39, s0, 4
	s_lshl_b32 s41, s0, 1
	v_readlane_b32 s0, v252, 0
	s_mov_b32 s48, s71
	s_mov_b32 s49, s73
	s_mov_b32 s50, s43
	s_mov_b32 s51, s70
	v_readlane_b32 s1, v255, 21
	s_branch .LBB0_426
